# code placement: the five long GEMM K-loop bodies start on a 64-byte boundary (.p2align 6)
# speedup vs baseline: 1.0040x; 1.0040x over previous
; template <class Epi, class Sched>
; __device__ __forceinline__ void gemm_phase(LAS unsigned char* lds, const Gemm g, const Sched& S, const Epi& E) {
;     ...
;         const char* nA = has_next ? PG8_ABASE(nxt) : cA; const char* nB = has_next ? PG8_BBASE(nxt) : cB;
; #pragma unroll 1
;         for (int t = 0; t < nt; t += 2) {
;             if constexpr (Epi::MIDT >= 0) {
;                 if (t == Epi::MIDT) { int fr_m = fr, fq_m = fq; asm volatile("" : "+v"(fr_m), "+v"(fq_m)); E.mid(acc, cur, wr, wc, fr_m, fq_m); }
;             }
;             const bool last = (t == nt - 2);
;             const char* a1 = cA + (size_t)(t + 1) * kstep;
;             const char* a2 = last ? nA : cA + (size_t)(t + 2) * kstep; const char* b2 = last ? nB : cB + (size_t)(t + 2) * kstep;
;             const char* a3 = a2 + kstep; const char* b3 = b2 + kstep;
;     ...
;         for (int a = 0; a < 2; ++a)
; #pragma unroll
;             for (int b = 0; b < 2; ++b)
; #pragma unroll
;                 for (int m = 0; m < 4; ++m)
; #pragma unroll
;                     for (int n = 0; n < 2; ++n) acc[a][b][m][n] = (f32x4){0.f, 0.f, 0.f, 0.f};
;         cur = nxt; cA = nA; cB = nB; ++ui;
.LBB0_121:
	s_ashr_i32 s87, s86, 31
	s_lshl_b64 s[6:7], s[86:87], 20
	s_add_u32 s92, s40, s6
	s_addc_u32 s93, s41, s7
	s_and_b64 s[6:7], s[90:91], exec
	s_cselect_b32 s8, s93, s1
	s_cselect_b32 s9, s92, s0
	s_ashr_i32 s89, s88, 31
	s_lshl_b64 s[6:7], s[88:89], 20
	s_add_u32 s94, s70, s6
	s_addc_u32 s95, s71, s7
	s_and_b64 s[6:7], s[90:91], exec
	s_cselect_b32 s10, s95, s5
	s_cselect_b32 s11, s94, s4
	s_add_u32 s0, s0, 0x80080
	s_addc_u32 s1, s1, 0
	s_add_u32 s34, s4, 0x100
	v_mov_b32_e32 v4, 0
	s_addc_u32 s35, s5, 0
	s_mov_b32 s87, -2
	v_mov_b32_e32 v5, v4
	v_mov_b32_e32 v6, v4
	v_mov_b32_e32 v7, v4
	v_mov_b32_e32 v0, v4
	v_mov_b32_e32 v1, v4
	v_mov_b32_e32 v2, v4
	v_mov_b32_e32 v3, v4
	v_mov_b32_e32 v8, v4
	v_mov_b32_e32 v9, v4
	v_mov_b32_e32 v10, v4
	v_mov_b32_e32 v11, v4
	v_mov_b32_e32 v12, v4
	v_mov_b32_e32 v13, v4
	v_mov_b32_e32 v14, v4
	v_mov_b32_e32 v15, v4
	v_mov_b32_e32 v16, v4
	v_mov_b32_e32 v17, v4
	v_mov_b32_e32 v18, v4
	v_mov_b32_e32 v19, v4
	v_mov_b32_e32 v20, v4
	v_mov_b32_e32 v21, v4
	v_mov_b32_e32 v22, v4
	v_mov_b32_e32 v23, v4
	v_mov_b32_e32 v24, v4
	v_mov_b32_e32 v25, v4
	v_mov_b32_e32 v26, v4
	v_mov_b32_e32 v27, v4
	v_mov_b32_e32 v28, v4
	v_mov_b32_e32 v29, v4
	v_mov_b32_e32 v30, v4
	v_mov_b32_e32 v31, v4
	v_mov_b32_e32 v68, v4
	v_mov_b32_e32 v69, v4
	v_mov_b32_e32 v70, v4
	v_mov_b32_e32 v71, v4
	v_mov_b32_e32 v64, v4
	v_mov_b32_e32 v65, v4
	v_mov_b32_e32 v66, v4
	v_mov_b32_e32 v67, v4
	v_mov_b32_e32 v72, v4
	v_mov_b32_e32 v73, v4
	v_mov_b32_e32 v74, v4
	v_mov_b32_e32 v75, v4
	v_mov_b32_e32 v76, v4
	v_mov_b32_e32 v77, v4
	v_mov_b32_e32 v78, v4
	v_mov_b32_e32 v79, v4
	v_mov_b32_e32 v80, v4
	v_mov_b32_e32 v81, v4
	v_mov_b32_e32 v82, v4
	v_mov_b32_e32 v83, v4
	v_mov_b32_e32 v84, v4
	v_mov_b32_e32 v85, v4
	v_mov_b32_e32 v86, v4
	v_mov_b32_e32 v87, v4
	v_mov_b32_e32 v88, v4
	v_mov_b32_e32 v89, v4
	v_mov_b32_e32 v90, v4
	v_mov_b32_e32 v91, v4
	v_mov_b32_e32 v92, v4
	v_mov_b32_e32 v93, v4
	v_mov_b32_e32 v94, v4
	v_mov_b32_e32 v95, v4
	v_mov_b32_e32 v36, v4
	v_mov_b32_e32 v37, v4
	v_mov_b32_e32 v38, v4
	v_mov_b32_e32 v39, v4
	v_mov_b32_e32 v32, v4
	v_mov_b32_e32 v33, v4
	v_mov_b32_e32 v34, v4
	v_mov_b32_e32 v35, v4
	v_mov_b32_e32 v40, v4
	v_mov_b32_e32 v41, v4
	v_mov_b32_e32 v42, v4
	v_mov_b32_e32 v43, v4
	v_mov_b32_e32 v44, v4
	v_mov_b32_e32 v45, v4
	v_mov_b32_e32 v46, v4
	v_mov_b32_e32 v47, v4
	v_mov_b32_e32 v48, v4
	v_mov_b32_e32 v49, v4
	v_mov_b32_e32 v50, v4
	v_mov_b32_e32 v51, v4
	v_mov_b32_e32 v52, v4
	v_mov_b32_e32 v53, v4
	v_mov_b32_e32 v54, v4
	v_mov_b32_e32 v55, v4
	v_mov_b32_e32 v56, v4
	v_mov_b32_e32 v57, v4
	v_mov_b32_e32 v58, v4
	v_mov_b32_e32 v59, v4
	v_mov_b32_e32 v60, v4
	v_mov_b32_e32 v61, v4
	v_mov_b32_e32 v62, v4
	v_mov_b32_e32 v63, v4
	v_mov_b32_e32 v100, v4
	v_mov_b32_e32 v101, v4
	v_mov_b32_e32 v102, v4
	v_mov_b32_e32 v103, v4
	v_mov_b32_e32 v96, v4
	v_mov_b32_e32 v97, v4
	v_mov_b32_e32 v98, v4
	v_mov_b32_e32 v99, v4
	v_mov_b32_e32 v104, v4
	v_mov_b32_e32 v105, v4
	v_mov_b32_e32 v106, v4
	v_mov_b32_e32 v107, v4
	v_mov_b32_e32 v108, v4
	v_mov_b32_e32 v109, v4
	v_mov_b32_e32 v110, v4
	v_mov_b32_e32 v111, v4
	v_mov_b32_e32 v112, v4
	v_mov_b32_e32 v113, v4
	v_mov_b32_e32 v114, v4
	v_mov_b32_e32 v115, v4
	v_mov_b32_e32 v116, v4
	v_mov_b32_e32 v117, v4
	v_mov_b32_e32 v118, v4
	v_mov_b32_e32 v119, v4
	v_mov_b32_e32 v120, v4
	v_mov_b32_e32 v121, v4
	v_mov_b32_e32 v122, v4
	v_mov_b32_e32 v123, v4
	v_mov_b32_e32 v124, v4
	v_mov_b32_e32 v125, v4
	v_mov_b32_e32 v126, v4
	v_mov_b32_e32 v127, v4
	.p2align 6

; template <class Epi, class Sched>
; __device__ __forceinline__ void gemm_phase(LAS unsigned char* lds, const Gemm g, const Sched& S, const Epi& E) {
;     ...
;         for (int a = 0; a < 2; ++a)
; #pragma unroll
;             for (int b = 0; b < 2; ++b)
; #pragma unroll
;                 for (int m = 0; m < 4; ++m)
; #pragma unroll
;                     for (int n = 0; n < 2; ++n) acc[a][b][m][n] = (f32x4){0.f, 0.f, 0.f, 0.f};
;         cur = nxt; cA = nA; cB = nB; ++ui;
.LBB0_751:
	s_lshl_b32 s31, s31, 8
	s_lshl_b32 s34, s34, 8
	s_or_b32 s31, s31, s22
	s_or_b32 s35, s34, 16
	s_or_b32 s45, s34, 32
	s_or_b32 s48, s34, 48
	s_or_b32 s49, s34, 0x80
	s_or_b32 s57, s34, 0x90
	s_or_b32 s70, s34, 0xa0
	s_or_b32 s71, s34, 0xb0
	v_mov_b32_e32 v2, v0
	v_mov_b32_e32 v3, v0
	s_add_u32 s72, s62, 0x100
	v_mov_b32_e32 v1, v0
	v_mov_b64_e32 v[6:7], v[2:3]
	v_mov_b64_e32 v[10:11], v[2:3]
	v_mov_b64_e32 v[22:23], v[2:3]
	v_mov_b64_e32 v[26:27], v[2:3]
	v_mov_b64_e32 v[38:39], v[2:3]
	v_mov_b64_e32 v[42:43], v[2:3]
	v_mov_b64_e32 v[54:55], v[2:3]
	v_mov_b64_e32 v[58:59], v[2:3]
	v_mov_b64_e32 v[14:15], v[2:3]
	v_mov_b64_e32 v[18:19], v[2:3]
	v_mov_b64_e32 v[30:31], v[2:3]
	v_mov_b64_e32 v[34:35], v[2:3]
	v_mov_b64_e32 v[46:47], v[2:3]
	v_mov_b64_e32 v[50:51], v[2:3]
	v_mov_b64_e32 v[62:63], v[2:3]
	v_mov_b64_e32 v[66:67], v[2:3]
	v_mov_b64_e32 v[70:71], v[2:3]
	v_mov_b64_e32 v[74:75], v[2:3]
	v_mov_b64_e32 v[86:87], v[2:3]
	v_mov_b64_e32 v[90:91], v[2:3]
	v_mov_b64_e32 v[102:103], v[2:3]
	v_mov_b64_e32 v[106:107], v[2:3]
	v_mov_b64_e32 v[118:119], v[2:3]
	v_mov_b64_e32 v[122:123], v[2:3]
	v_mov_b64_e32 v[78:79], v[2:3]
	v_mov_b64_e32 v[82:83], v[2:3]
	v_mov_b64_e32 v[94:95], v[2:3]
	v_mov_b64_e32 v[98:99], v[2:3]
	v_mov_b64_e32 v[110:111], v[2:3]
	v_mov_b64_e32 v[114:115], v[2:3]
	v_mov_b64_e32 v[126:127], v[2:3]
	v_mov_b64_e32 v[130:131], v[2:3]
	v_lshl_add_u64 v[148:149], s[60:61], 0, v[140:141]
	v_lshl_add_u64 v[150:151], s[60:61], 0, v[142:143]
	s_addc_u32 s73, s63, 0
	s_mov_b32 s74, -2
	s_mov_b64 s[62:63], 0
	v_mov_b64_e32 v[4:5], v[0:1]
	v_mov_b64_e32 v[8:9], v[0:1]
	v_mov_b64_e32 v[20:21], v[0:1]
	v_mov_b64_e32 v[24:25], v[0:1]
	v_mov_b64_e32 v[36:37], v[0:1]
	v_mov_b64_e32 v[40:41], v[0:1]
	v_mov_b64_e32 v[52:53], v[0:1]
	v_mov_b64_e32 v[56:57], v[0:1]
	v_mov_b64_e32 v[12:13], v[0:1]
	v_mov_b64_e32 v[16:17], v[0:1]
	v_mov_b64_e32 v[28:29], v[0:1]
	v_mov_b64_e32 v[32:33], v[0:1]
	v_mov_b64_e32 v[44:45], v[0:1]
	v_mov_b64_e32 v[48:49], v[0:1]
	v_mov_b64_e32 v[60:61], v[0:1]
	v_mov_b64_e32 v[64:65], v[0:1]
	v_mov_b64_e32 v[68:69], v[0:1]
	v_mov_b64_e32 v[72:73], v[0:1]
	v_mov_b64_e32 v[84:85], v[0:1]
	v_mov_b64_e32 v[88:89], v[0:1]
	v_mov_b64_e32 v[100:101], v[0:1]
	v_mov_b64_e32 v[104:105], v[0:1]
	v_mov_b64_e32 v[116:117], v[0:1]
	v_mov_b64_e32 v[120:121], v[0:1]
	v_mov_b64_e32 v[76:77], v[0:1]
	v_mov_b64_e32 v[80:81], v[0:1]
	v_mov_b64_e32 v[92:93], v[0:1]
	v_mov_b64_e32 v[96:97], v[0:1]
	v_mov_b64_e32 v[108:109], v[0:1]
	v_mov_b64_e32 v[112:113], v[0:1]
	v_mov_b64_e32 v[124:125], v[0:1]
	v_mov_b64_e32 v[128:129], v[0:1]
	s_branch .LBB0_753
	.p2align 6

; template <class Epi, class Sched>
; __device__ __forceinline__ void gemm_phase(LAS unsigned char* lds, const Gemm g, const Sched& S, const Epi& E) {
;     ...
;         const char* nA = has_next ? PG8_ABASE(nxt) : cA; const char* nB = has_next ? PG8_BBASE(nxt) : cB;
; #pragma unroll 1
;         for (int t = 0; t < nt; t += 2) {
;             if constexpr (Epi::MIDT >= 0) {
;                 if (t == Epi::MIDT) { int fr_m = fr, fq_m = fq; asm volatile("" : "+v"(fr_m), "+v"(fq_m)); E.mid(acc, cur, wr, wc, fr_m, fq_m); }
;             }
;             const bool last = (t == nt - 2);
;             const char* a1 = cA + (size_t)(t + 1) * kstep;
;             const char* a2 = last ? nA : cA + (size_t)(t + 2) * kstep; const char* b2 = last ? nB : cB + (size_t)(t + 2) * kstep;
;             const char* a3 = a2 + kstep; const char* b3 = b2 + kstep;
;     ...
;         for (int a = 0; a < 2; ++a)
; #pragma unroll
;             for (int b = 0; b < 2; ++b)
; #pragma unroll
;                 for (int m = 0; m < 4; ++m)
; #pragma unroll
;                     for (int n = 0; n < 2; ++n) acc[a][b][m][n] = (f32x4){0.f, 0.f, 0.f, 0.f};
;         cur = nxt; cA = nA; cB = nB; ++ui;
.LBB0_828:
	s_ashr_i32 s39, s38, 31
	s_lshl_b64 s[12:13], s[38:39], 20
	s_add_u32 s52, s50, s12
	s_addc_u32 s53, s51, s13
	s_and_b64 s[12:13], s[0:1], exec
	s_cselect_b32 s12, s53, s61
	s_cselect_b32 s13, s52, s60
	s_ashr_i32 s43, s42, 31
	s_lshl_b64 s[30:31], s[42:43], 20
	s_add_u32 s54, s16, s30
	s_addc_u32 s55, s17, s31
	s_and_b64 s[30:31], s[0:1], exec
	s_cselect_b32 s29, s55, s63
	s_cselect_b32 s30, s54, s62
	s_add_u32 s60, s60, 0x80080
	s_addc_u32 s61, s61, 0
	s_add_u32 s31, s62, 0x100
	v_mov_b32_e32 v0, 0
	s_addc_u32 s34, s63, 0
	s_mov_b32 s35, -2
	s_waitcnt lgkmcnt(0)
	v_mov_b32_e32 v1, v0
	v_mov_b32_e32 v2, v0
	v_mov_b32_e32 v3, v0
	v_mov_b32_e32 v4, v0
	v_mov_b32_e32 v5, v0
	v_mov_b32_e32 v6, v0
	v_mov_b32_e32 v7, v0
	v_mov_b32_e32 v16, v0
	v_mov_b32_e32 v17, v0
	v_mov_b32_e32 v18, v0
	v_mov_b32_e32 v19, v0
	v_mov_b32_e32 v20, v0
	v_mov_b32_e32 v21, v0
	v_mov_b32_e32 v22, v0
	v_mov_b32_e32 v23, v0
	v_mov_b32_e32 v32, v0
	v_mov_b32_e32 v33, v0
	v_mov_b32_e32 v34, v0
	v_mov_b32_e32 v35, v0
	v_mov_b32_e32 v36, v0
	v_mov_b32_e32 v37, v0
	v_mov_b32_e32 v38, v0
	v_mov_b32_e32 v39, v0
	v_mov_b32_e32 v48, v0
	v_mov_b32_e32 v49, v0
	v_mov_b32_e32 v50, v0
	v_mov_b32_e32 v51, v0
	v_mov_b32_e32 v52, v0
	v_mov_b32_e32 v53, v0
	v_mov_b32_e32 v54, v0
	v_mov_b32_e32 v55, v0
	v_mov_b32_e32 v8, v0
	v_mov_b32_e32 v9, v0
	v_mov_b32_e32 v10, v0
	v_mov_b32_e32 v11, v0
	v_mov_b32_e32 v12, v0
	v_mov_b32_e32 v13, v0
	v_mov_b32_e32 v14, v0
	v_mov_b32_e32 v15, v0
	v_mov_b32_e32 v24, v0
	v_mov_b32_e32 v25, v0
	v_mov_b32_e32 v26, v0
	v_mov_b32_e32 v27, v0
	v_mov_b32_e32 v28, v0
	v_mov_b32_e32 v29, v0
	v_mov_b32_e32 v30, v0
	v_mov_b32_e32 v31, v0
	v_mov_b32_e32 v40, v0
	v_mov_b32_e32 v41, v0
	v_mov_b32_e32 v42, v0
	v_mov_b32_e32 v43, v0
	v_mov_b32_e32 v44, v0
	v_mov_b32_e32 v45, v0
	v_mov_b32_e32 v46, v0
	v_mov_b32_e32 v47, v0
	v_mov_b32_e32 v56, v0
	v_mov_b32_e32 v57, v0
	v_mov_b32_e32 v58, v0
	v_mov_b32_e32 v59, v0
	v_mov_b32_e32 v60, v0
	v_mov_b32_e32 v61, v0
	v_mov_b32_e32 v62, v0
	v_mov_b32_e32 v63, v0
	v_mov_b32_e32 v64, v0
	v_mov_b32_e32 v65, v0
	v_mov_b32_e32 v66, v0
	v_mov_b32_e32 v67, v0
	v_mov_b32_e32 v68, v0
	v_mov_b32_e32 v69, v0
	v_mov_b32_e32 v70, v0
	v_mov_b32_e32 v71, v0
	v_mov_b32_e32 v80, v0
	v_mov_b32_e32 v81, v0
	v_mov_b32_e32 v82, v0
	v_mov_b32_e32 v83, v0
	v_mov_b32_e32 v84, v0
	v_mov_b32_e32 v85, v0
	v_mov_b32_e32 v86, v0
	v_mov_b32_e32 v87, v0
	v_mov_b32_e32 v96, v0
	v_mov_b32_e32 v97, v0
	v_mov_b32_e32 v98, v0
	v_mov_b32_e32 v99, v0
	v_mov_b32_e32 v100, v0
	v_mov_b32_e32 v101, v0
	v_mov_b32_e32 v102, v0
	v_mov_b32_e32 v103, v0
	v_mov_b32_e32 v112, v0
	v_mov_b32_e32 v113, v0
	v_mov_b32_e32 v114, v0
	v_mov_b32_e32 v115, v0
	v_mov_b32_e32 v116, v0
	v_mov_b32_e32 v117, v0
	v_mov_b32_e32 v118, v0
	v_mov_b32_e32 v119, v0
	v_mov_b32_e32 v72, v0
	v_mov_b32_e32 v73, v0
	v_mov_b32_e32 v74, v0
	v_mov_b32_e32 v75, v0
	v_mov_b32_e32 v76, v0
	v_mov_b32_e32 v77, v0
	v_mov_b32_e32 v78, v0
	v_mov_b32_e32 v79, v0
	v_mov_b32_e32 v88, v0
	v_mov_b32_e32 v89, v0
	v_mov_b32_e32 v90, v0
	v_mov_b32_e32 v91, v0
	v_mov_b32_e32 v92, v0
	v_mov_b32_e32 v93, v0
	v_mov_b32_e32 v94, v0
	v_mov_b32_e32 v95, v0
	v_mov_b32_e32 v104, v0
	v_mov_b32_e32 v105, v0
	v_mov_b32_e32 v106, v0
	v_mov_b32_e32 v107, v0
	v_mov_b32_e32 v108, v0
	v_mov_b32_e32 v109, v0
	v_mov_b32_e32 v110, v0
	v_mov_b32_e32 v111, v0
	v_mov_b32_e32 v120, v0
	v_mov_b32_e32 v121, v0
	v_mov_b32_e32 v122, v0
	v_mov_b32_e32 v123, v0
	v_mov_b32_e32 v124, v0
	v_mov_b32_e32 v125, v0
	v_mov_b32_e32 v126, v0
	v_mov_b32_e32 v127, v0
	.p2align 6

; template <class Epi, class Sched>
; __device__ __forceinline__ void gemm_phase(LAS unsigned char* lds, const Gemm g, const Sched& S, const Epi& E) {
;     ...
;         const char* nA = has_next ? PG8_ABASE(nxt) : cA; const char* nB = has_next ? PG8_BBASE(nxt) : cB;
; #pragma unroll 1
;         for (int t = 0; t < nt; t += 2) {
;             if constexpr (Epi::MIDT >= 0) {
;                 if (t == Epi::MIDT) { int fr_m = fr, fq_m = fq; asm volatile("" : "+v"(fr_m), "+v"(fq_m)); E.mid(acc, cur, wr, wc, fr_m, fq_m); }
;             }
;             const bool last = (t == nt - 2);
;             const char* a1 = cA + (size_t)(t + 1) * kstep;
;             const char* a2 = last ? nA : cA + (size_t)(t + 2) * kstep; const char* b2 = last ? nB : cB + (size_t)(t + 2) * kstep;
;             const char* a3 = a2 + kstep; const char* b3 = b2 + kstep;
;     ...
;         for (int a = 0; a < 2; ++a)
; #pragma unroll
;             for (int b = 0; b < 2; ++b)
; #pragma unroll
;                 for (int m = 0; m < 4; ++m)
; #pragma unroll
;                     for (int n = 0; n < 2; ++n) acc[a][b][m][n] = (f32x4){0.f, 0.f, 0.f, 0.f};
;         cur = nxt; cA = nA; cB = nB; ++ui;
.LBB0_922:
	s_ashr_i32 s53, s52, 31
	s_lshl_b64 s[12:13], s[52:53], 20
	s_add_u32 s56, s74, s12
	s_addc_u32 s57, s75, s13
	s_and_b64 s[12:13], s[6:7], exec
	s_cselect_b32 s12, s57, s1
	s_cselect_b32 s13, s56, s0
	s_ashr_i32 s55, s54, 31
	s_lshl_b64 s[58:59], s[54:55], 20
	s_add_u32 s58, s46, s58
	s_addc_u32 s59, s47, s59
	s_and_b64 s[6:7], s[6:7], exec
	s_cselect_b32 s53, s59, s5
	s_cselect_b32 s55, s58, s4
	s_add_u32 s0, s0, 0x80080
	s_addc_u32 s1, s1, 0
	s_add_u32 s60, s4, 0x100
	v_mov_b32_e32 v4, 0
	s_addc_u32 s61, s5, 0
	s_mov_b32 s62, -2
	v_mov_b32_e32 v5, v4
	v_mov_b32_e32 v6, v4
	v_mov_b32_e32 v7, v4
	v_mov_b32_e32 v0, v4
	v_mov_b32_e32 v1, v4
	v_mov_b32_e32 v2, v4
	v_mov_b32_e32 v3, v4
	v_mov_b32_e32 v16, v4
	v_mov_b32_e32 v17, v4
	v_mov_b32_e32 v18, v4
	v_mov_b32_e32 v19, v4
	v_mov_b32_e32 v20, v4
	v_mov_b32_e32 v21, v4
	v_mov_b32_e32 v22, v4
	v_mov_b32_e32 v23, v4
	v_mov_b32_e32 v32, v4
	v_mov_b32_e32 v33, v4
	v_mov_b32_e32 v34, v4
	v_mov_b32_e32 v35, v4
	v_mov_b32_e32 v36, v4
	v_mov_b32_e32 v37, v4
	v_mov_b32_e32 v38, v4
	v_mov_b32_e32 v39, v4
	v_mov_b32_e32 v48, v4
	v_mov_b32_e32 v49, v4
	v_mov_b32_e32 v50, v4
	v_mov_b32_e32 v51, v4
	v_mov_b32_e32 v52, v4
	v_mov_b32_e32 v53, v4
	v_mov_b32_e32 v54, v4
	v_mov_b32_e32 v55, v4
	v_mov_b32_e32 v8, v4
	v_mov_b32_e32 v9, v4
	v_mov_b32_e32 v10, v4
	v_mov_b32_e32 v11, v4
	v_mov_b32_e32 v12, v4
	v_mov_b32_e32 v13, v4
	v_mov_b32_e32 v14, v4
	v_mov_b32_e32 v15, v4
	v_mov_b32_e32 v24, v4
	v_mov_b32_e32 v25, v4
	v_mov_b32_e32 v26, v4
	v_mov_b32_e32 v27, v4
	v_mov_b32_e32 v28, v4
	v_mov_b32_e32 v29, v4
	v_mov_b32_e32 v30, v4
	v_mov_b32_e32 v31, v4
	v_mov_b32_e32 v40, v4
	v_mov_b32_e32 v41, v4
	v_mov_b32_e32 v42, v4
	v_mov_b32_e32 v43, v4
	v_mov_b32_e32 v44, v4
	v_mov_b32_e32 v45, v4
	v_mov_b32_e32 v46, v4
	v_mov_b32_e32 v47, v4
	v_mov_b32_e32 v56, v4
	v_mov_b32_e32 v57, v4
	v_mov_b32_e32 v58, v4
	v_mov_b32_e32 v59, v4
	v_mov_b32_e32 v60, v4
	v_mov_b32_e32 v61, v4
	v_mov_b32_e32 v62, v4
	v_mov_b32_e32 v63, v4
	v_mov_b32_e32 v100, v4
	v_mov_b32_e32 v101, v4
	v_mov_b32_e32 v102, v4
	v_mov_b32_e32 v103, v4
	v_mov_b32_e32 v80, v4
	v_mov_b32_e32 v81, v4
	v_mov_b32_e32 v82, v4
	v_mov_b32_e32 v83, v4
	v_mov_b32_e32 v112, v4
	v_mov_b32_e32 v113, v4
	v_mov_b32_e32 v114, v4
	v_mov_b32_e32 v115, v4
	v_mov_b32_e32 v116, v4
	v_mov_b32_e32 v117, v4
	v_mov_b32_e32 v118, v4
	v_mov_b32_e32 v119, v4
	v_mov_b32_e32 v128, v4
	v_mov_b32_e32 v129, v4
	v_mov_b32_e32 v130, v4
	v_mov_b32_e32 v131, v4
	v_mov_b32_e32 v132, v4
	v_mov_b32_e32 v133, v4
	v_mov_b32_e32 v134, v4
	v_mov_b32_e32 v135, v4
	v_mov_b32_e32 v144, v4
	v_mov_b32_e32 v145, v4
	v_mov_b32_e32 v146, v4
	v_mov_b32_e32 v147, v4
	v_mov_b32_e32 v152, v4
	v_mov_b32_e32 v153, v4
	v_mov_b32_e32 v154, v4
	v_mov_b32_e32 v155, v4
	v_mov_b32_e32 v104, v4
	v_mov_b32_e32 v105, v4
	v_mov_b32_e32 v106, v4
	v_mov_b32_e32 v107, v4
	v_mov_b32_e32 v108, v4
	v_mov_b32_e32 v109, v4
	v_mov_b32_e32 v110, v4
	v_mov_b32_e32 v111, v4
	v_mov_b32_e32 v120, v4
	v_mov_b32_e32 v121, v4
	v_mov_b32_e32 v122, v4
	v_mov_b32_e32 v123, v4
	v_mov_b32_e32 v124, v4
	v_mov_b32_e32 v125, v4
	v_mov_b32_e32 v126, v4
	v_mov_b32_e32 v127, v4
	v_mov_b32_e32 v136, v4
	v_mov_b32_e32 v137, v4
	v_mov_b32_e32 v138, v4
	v_mov_b32_e32 v139, v4
	v_mov_b32_e32 v140, v4
	v_mov_b32_e32 v141, v4
	v_mov_b32_e32 v142, v4
	v_mov_b32_e32 v143, v4
	v_mov_b32_e32 v148, v4
	v_mov_b32_e32 v149, v4
	v_mov_b32_e32 v150, v4
	v_mov_b32_e32 v151, v4
	v_mov_b32_e32 v156, v4
	v_mov_b32_e32 v157, v4
	v_mov_b32_e32 v158, v4
	v_mov_b32_e32 v159, v4
	.p2align 6

; template <class Epi, class Sched>
; __device__ __forceinline__ void gemm_phase(LAS unsigned char* lds, const Gemm g, const Sched& S, const Epi& E) {
;     ...
;         for (int a = 0; a < 2; ++a)
; #pragma unroll
;             for (int b = 0; b < 2; ++b)
; #pragma unroll
;                 for (int m = 0; m < 4; ++m)
; #pragma unroll
;                     for (int n = 0; n < 2; ++n) acc[a][b][m][n] = (f32x4){0.f, 0.f, 0.f, 0.f};
;         cur = nxt; cA = nA; cB = nB; ++ui;
.LBB0_1076:
	v_mov_b32_e32 v0, 0
	s_mov_b32 s1, -2
	s_mov_b64 s[4:5], s[20:21]
	v_mov_b32_e32 v1, v0
	v_mov_b32_e32 v2, v0
	v_mov_b32_e32 v3, v0
	v_mov_b32_e32 v4, v0
	v_mov_b32_e32 v5, v0
	v_mov_b32_e32 v6, v0
	v_mov_b32_e32 v7, v0
	v_mov_b32_e32 v16, v0
	v_mov_b32_e32 v17, v0
	v_mov_b32_e32 v18, v0
	v_mov_b32_e32 v19, v0
	v_mov_b32_e32 v20, v0
	v_mov_b32_e32 v21, v0
	v_mov_b32_e32 v22, v0
	v_mov_b32_e32 v23, v0
	v_mov_b32_e32 v32, v0
	v_mov_b32_e32 v33, v0
	v_mov_b32_e32 v34, v0
	v_mov_b32_e32 v35, v0
	v_mov_b32_e32 v36, v0
	v_mov_b32_e32 v37, v0
	v_mov_b32_e32 v38, v0
	v_mov_b32_e32 v39, v0
	v_mov_b32_e32 v48, v0
	v_mov_b32_e32 v49, v0
	v_mov_b32_e32 v50, v0
	v_mov_b32_e32 v51, v0
	v_mov_b32_e32 v52, v0
	v_mov_b32_e32 v53, v0
	v_mov_b32_e32 v54, v0
	v_mov_b32_e32 v55, v0
	v_mov_b32_e32 v8, v0
	v_mov_b32_e32 v9, v0
	v_mov_b32_e32 v10, v0
	v_mov_b32_e32 v11, v0
	v_mov_b32_e32 v12, v0
	v_mov_b32_e32 v13, v0
	v_mov_b32_e32 v14, v0
	v_mov_b32_e32 v15, v0
	v_mov_b32_e32 v24, v0
	v_mov_b32_e32 v25, v0
	v_mov_b32_e32 v26, v0
	v_mov_b32_e32 v27, v0
	v_mov_b32_e32 v28, v0
	v_mov_b32_e32 v29, v0
	v_mov_b32_e32 v30, v0
	v_mov_b32_e32 v31, v0
	v_mov_b32_e32 v40, v0
	v_mov_b32_e32 v41, v0
	v_mov_b32_e32 v42, v0
	v_mov_b32_e32 v43, v0
	v_mov_b32_e32 v44, v0
	v_mov_b32_e32 v45, v0
	v_mov_b32_e32 v46, v0
	v_mov_b32_e32 v47, v0
	v_mov_b32_e32 v56, v0
	v_mov_b32_e32 v57, v0
	v_mov_b32_e32 v58, v0
	v_mov_b32_e32 v59, v0
	v_mov_b32_e32 v60, v0
	v_mov_b32_e32 v61, v0
	v_mov_b32_e32 v62, v0
	v_mov_b32_e32 v63, v0
	v_mov_b32_e32 v64, v0
	v_mov_b32_e32 v65, v0
	v_mov_b32_e32 v66, v0
	v_mov_b32_e32 v67, v0
	v_mov_b32_e32 v68, v0
	v_mov_b32_e32 v69, v0
	v_mov_b32_e32 v70, v0
	v_mov_b32_e32 v71, v0
	v_mov_b32_e32 v80, v0
	v_mov_b32_e32 v81, v0
	v_mov_b32_e32 v82, v0
	v_mov_b32_e32 v83, v0
	v_mov_b32_e32 v84, v0
	v_mov_b32_e32 v85, v0
	v_mov_b32_e32 v86, v0
	v_mov_b32_e32 v87, v0
	v_mov_b32_e32 v96, v0
	v_mov_b32_e32 v97, v0
	v_mov_b32_e32 v98, v0
	v_mov_b32_e32 v99, v0
	v_mov_b32_e32 v100, v0
	v_mov_b32_e32 v101, v0
	v_mov_b32_e32 v102, v0
	v_mov_b32_e32 v103, v0
	v_mov_b32_e32 v112, v0
	v_mov_b32_e32 v113, v0
	v_mov_b32_e32 v114, v0
	v_mov_b32_e32 v115, v0
	v_mov_b32_e32 v116, v0
	v_mov_b32_e32 v117, v0
	v_mov_b32_e32 v118, v0
	v_mov_b32_e32 v119, v0
	v_mov_b32_e32 v72, v0
	v_mov_b32_e32 v73, v0
	v_mov_b32_e32 v74, v0
	v_mov_b32_e32 v75, v0
	v_mov_b32_e32 v76, v0
	v_mov_b32_e32 v77, v0
	v_mov_b32_e32 v78, v0
	v_mov_b32_e32 v79, v0
	v_mov_b32_e32 v88, v0
	v_mov_b32_e32 v89, v0
	v_mov_b32_e32 v90, v0
	v_mov_b32_e32 v91, v0
	v_mov_b32_e32 v92, v0
	v_mov_b32_e32 v93, v0
	v_mov_b32_e32 v94, v0
	v_mov_b32_e32 v95, v0
	v_mov_b32_e32 v104, v0
	v_mov_b32_e32 v105, v0
	v_mov_b32_e32 v106, v0
	v_mov_b32_e32 v107, v0
	v_mov_b32_e32 v108, v0
	v_mov_b32_e32 v109, v0
	v_mov_b32_e32 v110, v0
	v_mov_b32_e32 v111, v0
	v_mov_b32_e32 v120, v0
	v_mov_b32_e32 v121, v0
	v_mov_b32_e32 v122, v0
	v_mov_b32_e32 v123, v0
	v_mov_b32_e32 v124, v0
	v_mov_b32_e32 v125, v0
	v_mov_b32_e32 v126, v0
	v_mov_b32_e32 v127, v0
	.p2align 6
